# P12 epilogue stores of HID2: plain instead of nt (plus P12 epilogue-load prefetch)
# speedup vs baseline: 1.0076x; 1.0017x over previous
.Lp12_nopf:
	v_lshl_add_u64 v[174:175], s[24:25], 0, v[158:159]
	s_add_i32 m0, s43, 0xc000
	ds_read_b128 v[166:169], v173
	ds_read_b128 v[178:181], v173 offset:1024
	ds_read_b128 v[182:185], v173 offset:2048
	ds_read_b128 v[186:189], v173 offset:3072
	ds_read_b128 v[190:193], v173 offset:4096
	ds_read_b128 v[194:197], v173 offset:5120
	ds_read_b128 v[198:201], v173 offset:6144
	ds_read_b128 v[202:205], v173 offset:7168
	global_load_lds_dwordx4 v[174:175], off
	v_lshl_add_u64 v[174:175], s[24:25], 0, v[160:161]
	s_add_i32 m0, s43, 0xe000
	s_nop 0
	global_load_lds_dwordx4 v[174:175], off
	s_waitcnt lgkmcnt(8)
	s_barrier
	s_waitcnt lgkmcnt(0)
	s_setprio 1
	s_waitcnt lgkmcnt(0)
	v_mfma_f32_16x16x32_bf16 v[126:129], v[130:133], v[166:169], v[126:129]
	v_mfma_f32_16x16x32_bf16 v[122:125], v[138:141], v[166:169], v[122:125]
	v_mfma_f32_16x16x32_bf16 v[110:113], v[130:133], v[182:185], v[110:113]
	v_mfma_f32_16x16x32_bf16 v[106:109], v[138:141], v[182:185], v[106:109]
	v_mfma_f32_16x16x32_bf16 v[94:97], v[130:133], v[190:193], v[94:97]
	v_mfma_f32_16x16x32_bf16 v[90:93], v[138:141], v[190:193], v[90:93]
	v_mfma_f32_16x16x32_bf16 v[78:81], v[130:133], v[198:201], v[78:81]
	v_mfma_f32_16x16x32_bf16 v[74:77], v[138:141], v[198:201], v[74:77]
	v_mfma_f32_16x16x32_bf16 v[126:129], v[134:137], v[178:181], v[126:129]
	v_mfma_f32_16x16x32_bf16 v[122:125], v[142:145], v[178:181], v[122:125]
	v_mfma_f32_16x16x32_bf16 v[110:113], v[134:137], v[186:189], v[110:113]
	v_mfma_f32_16x16x32_bf16 v[106:109], v[142:145], v[186:189], v[106:109]
	v_mfma_f32_16x16x32_bf16 v[94:97], v[134:137], v[194:197], v[94:97]
	v_mfma_f32_16x16x32_bf16 v[90:93], v[142:145], v[194:197], v[90:93]
	v_mfma_f32_16x16x32_bf16 v[78:81], v[134:137], v[202:205], v[78:81]
	v_mfma_f32_16x16x32_bf16 v[74:77], v[142:145], v[202:205], v[74:77]
	s_setprio 0
	s_barrier
	s_add_i32 s20, s54, s42
	v_lshl_add_u64 v[174:175], s[34:35], 0, v[150:151]
	s_mov_b32 m0, s20
	ds_read_b128 v[206:209], v177
	ds_read_b128 v[210:213], v177 offset:1024
	ds_read_b128 v[214:217], v177 offset:2048
	ds_read_b128 v[218:221], v177 offset:3072
	global_load_lds_dwordx4 v[174:175], off
	v_lshl_add_u64 v[222:223], s[34:35], 0, v[146:147]
	s_add_i32 m0, s20, 0x2000
	s_nop 0
	global_load_lds_dwordx4 v[222:223], off
	s_barrier
	s_waitcnt lgkmcnt(0)
	s_setprio 1
	s_waitcnt lgkmcnt(0)
	v_mfma_f32_16x16x32_bf16 v[118:121], v[206:209], v[166:169], v[118:121]
	v_mfma_f32_16x16x32_bf16 v[114:117], v[214:217], v[166:169], v[114:117]
	v_mfma_f32_16x16x32_bf16 v[102:105], v[206:209], v[182:185], v[102:105]
	v_mfma_f32_16x16x32_bf16 v[98:101], v[214:217], v[182:185], v[98:101]
	v_mfma_f32_16x16x32_bf16 v[86:89], v[206:209], v[190:193], v[86:89]
	v_mfma_f32_16x16x32_bf16 v[82:85], v[214:217], v[190:193], v[82:85]
	v_mfma_f32_16x16x32_bf16 v[70:73], v[206:209], v[198:201], v[70:73]
	v_mfma_f32_16x16x32_bf16 v[66:69], v[214:217], v[198:201], v[66:69]
	v_mfma_f32_16x16x32_bf16 v[118:121], v[210:213], v[178:181], v[118:121]
	v_mfma_f32_16x16x32_bf16 v[114:117], v[218:221], v[178:181], v[114:117]
	v_mfma_f32_16x16x32_bf16 v[102:105], v[210:213], v[186:189], v[102:105]
	v_mfma_f32_16x16x32_bf16 v[98:101], v[218:221], v[186:189], v[98:101]
	v_mfma_f32_16x16x32_bf16 v[86:89], v[210:213], v[194:197], v[86:89]
	v_mfma_f32_16x16x32_bf16 v[82:85], v[218:221], v[194:197], v[82:85]
	v_mfma_f32_16x16x32_bf16 v[70:73], v[210:213], v[202:205], v[70:73]
	v_mfma_f32_16x16x32_bf16 v[66:69], v[218:221], v[202:205], v[66:69]
	s_setprio 0
	s_mov_b32 m0, s43
	v_lshl_add_u64 v[224:225], s[18:19], 0, v[152:153]
	s_barrier
	ds_read_b128 v[166:169], v173 offset:16384
	ds_read_b128 v[178:181], v173 offset:17408
	ds_read_b128 v[182:185], v173 offset:18432
	ds_read_b128 v[186:189], v173 offset:19456
	ds_read_b128 v[190:193], v173 offset:20480
	ds_read_b128 v[194:197], v173 offset:21504
	ds_read_b128 v[198:201], v173 offset:22528
	ds_read_b128 v[202:205], v173 offset:23552
	global_load_lds_dwordx4 v[224:225], off
	v_lshl_add_u64 v[226:227], s[18:19], 0, v[148:149]
	s_mov_b32 m0, s44
	s_nop 0
	global_load_lds_dwordx4 v[226:227], off
	s_barrier
	s_waitcnt lgkmcnt(0)
	s_setprio 1
	s_waitcnt lgkmcnt(0)
	v_mfma_f32_16x16x32_bf16 v[62:65], v[130:133], v[166:169], v[62:65]
	v_mfma_f32_16x16x32_bf16 v[58:61], v[138:141], v[166:169], v[58:61]
	v_mfma_f32_16x16x32_bf16 v[46:49], v[130:133], v[182:185], v[46:49]
	v_mfma_f32_16x16x32_bf16 v[42:45], v[138:141], v[182:185], v[42:45]
	v_mfma_f32_16x16x32_bf16 v[30:33], v[130:133], v[190:193], v[30:33]
	v_mfma_f32_16x16x32_bf16 v[26:29], v[138:141], v[190:193], v[26:29]
	v_mfma_f32_16x16x32_bf16 v[14:17], v[130:133], v[198:201], v[14:17]
	v_mfma_f32_16x16x32_bf16 v[10:13], v[138:141], v[198:201], v[10:13]
	v_mfma_f32_16x16x32_bf16 v[62:65], v[134:137], v[178:181], v[62:65]
	v_mfma_f32_16x16x32_bf16 v[58:61], v[142:145], v[178:181], v[58:61]
	v_mfma_f32_16x16x32_bf16 v[46:49], v[134:137], v[186:189], v[46:49]
	v_mfma_f32_16x16x32_bf16 v[42:45], v[142:145], v[186:189], v[42:45]
	v_mfma_f32_16x16x32_bf16 v[30:33], v[134:137], v[194:197], v[30:33]
	v_mfma_f32_16x16x32_bf16 v[26:29], v[142:145], v[194:197], v[26:29]
	v_mfma_f32_16x16x32_bf16 v[14:17], v[134:137], v[202:205], v[14:17]
	v_mfma_f32_16x16x32_bf16 v[10:13], v[142:145], v[202:205], v[10:13]
	s_setprio 0
	s_barrier
	s_add_u32 s20, s34, 0x40000
	s_addc_u32 s21, s35, 0
	s_add_i32 s64, s55, s42
	v_lshl_add_u64 v[130:131], s[20:21], 0, v[150:151]
	s_mov_b32 m0, s64
	s_nop 0
	global_load_lds_dwordx4 v[130:131], off
	v_lshl_add_u64 v[130:131], s[20:21], 0, v[146:147]
	s_add_i32 m0, s64, 0x2000
	s_nop 0
	global_load_lds_dwordx4 v[130:131], off
	s_waitcnt vmcnt(6)
	s_barrier
	s_setprio 1
	v_mfma_f32_16x16x32_bf16 v[54:57], v[206:209], v[166:169], v[54:57]
	v_mfma_f32_16x16x32_bf16 v[50:53], v[214:217], v[166:169], v[50:53]
	v_mfma_f32_16x16x32_bf16 v[38:41], v[206:209], v[182:185], v[38:41]
	v_mfma_f32_16x16x32_bf16 v[34:37], v[214:217], v[182:185], v[34:37]
	v_mfma_f32_16x16x32_bf16 v[22:25], v[206:209], v[190:193], v[22:25]
	v_mfma_f32_16x16x32_bf16 v[18:21], v[214:217], v[190:193], v[18:21]
	v_mfma_f32_16x16x32_bf16 v[6:9], v[206:209], v[198:201], v[6:9]
	v_mfma_f32_16x16x32_bf16 v[2:5], v[214:217], v[198:201], v[2:5]
	v_mfma_f32_16x16x32_bf16 v[54:57], v[210:213], v[178:181], v[54:57]
	v_mfma_f32_16x16x32_bf16 v[50:53], v[218:221], v[178:181], v[50:53]
	v_mfma_f32_16x16x32_bf16 v[38:41], v[210:213], v[186:189], v[38:41]
	v_mfma_f32_16x16x32_bf16 v[34:37], v[218:221], v[186:189], v[34:37]
	v_mfma_f32_16x16x32_bf16 v[22:25], v[210:213], v[194:197], v[22:25]
	v_mfma_f32_16x16x32_bf16 v[18:21], v[218:221], v[194:197], v[18:21]
	v_mfma_f32_16x16x32_bf16 v[6:9], v[210:213], v[202:205], v[6:9]
	v_mfma_f32_16x16x32_bf16 v[2:5], v[218:221], v[202:205], v[2:5]
	s_setprio 0
	s_add_i32 s20, 0, 0x18000
	v_add_u32_e32 v142, s20, v157
	s_barrier
	ds_read_b128 v[130:133], v142
	ds_read_b128 v[134:137], v142 offset:1024
	ds_read_b128 v[138:141], v142 offset:2048
	ds_read_b128 v[142:145], v142 offset:3072
	s_add_u32 s18, s18, 0x40000
	s_addc_u32 s19, s19, 0
	s_mov_b32 m0, s45
	v_lshl_add_u64 v[206:207], s[18:19], 0, v[152:153]
	ds_read_b128 v[166:169], v173 offset:32768
	ds_read_b128 v[178:181], v173 offset:33792
	ds_read_b128 v[182:185], v173 offset:34816
	ds_read_b128 v[186:189], v173 offset:35840
	ds_read_b128 v[190:193], v173 offset:36864
	ds_read_b128 v[194:197], v173 offset:37888
	ds_read_b128 v[198:201], v173 offset:38912
	ds_read_b128 v[202:205], v173 offset:39936
	global_load_lds_dwordx4 v[206:207], off
	v_lshl_add_u64 v[206:207], s[18:19], 0, v[148:149]
	s_mov_b32 m0, s46
	s_nop 0
	global_load_lds_dwordx4 v[206:207], off
	s_waitcnt lgkmcnt(8)
	s_barrier
	s_waitcnt lgkmcnt(0)
	s_setprio 1
	s_waitcnt lgkmcnt(0)
	v_mfma_f32_16x16x32_bf16 v[126:129], v[130:133], v[166:169], v[126:129]
	v_mfma_f32_16x16x32_bf16 v[122:125], v[138:141], v[166:169], v[122:125]
	v_mfma_f32_16x16x32_bf16 v[110:113], v[130:133], v[182:185], v[110:113]
	v_mfma_f32_16x16x32_bf16 v[106:109], v[138:141], v[182:185], v[106:109]
	v_mfma_f32_16x16x32_bf16 v[94:97], v[130:133], v[190:193], v[94:97]
	v_mfma_f32_16x16x32_bf16 v[90:93], v[138:141], v[190:193], v[90:93]
	v_mfma_f32_16x16x32_bf16 v[78:81], v[130:133], v[198:201], v[78:81]
	v_mfma_f32_16x16x32_bf16 v[74:77], v[138:141], v[198:201], v[74:77]
	v_mfma_f32_16x16x32_bf16 v[126:129], v[134:137], v[178:181], v[126:129]
	v_mfma_f32_16x16x32_bf16 v[122:125], v[142:145], v[178:181], v[122:125]
	v_mfma_f32_16x16x32_bf16 v[110:113], v[134:137], v[186:189], v[110:113]
	v_mfma_f32_16x16x32_bf16 v[106:109], v[142:145], v[186:189], v[106:109]
	v_mfma_f32_16x16x32_bf16 v[94:97], v[134:137], v[194:197], v[94:97]
	v_mfma_f32_16x16x32_bf16 v[90:93], v[142:145], v[194:197], v[90:93]
	v_mfma_f32_16x16x32_bf16 v[78:81], v[134:137], v[202:205], v[78:81]
	v_mfma_f32_16x16x32_bf16 v[74:77], v[142:145], v[202:205], v[74:77]
	s_setprio 0
	s_barrier
	s_add_i32 s21, 0, 0x1c000
	s_add_i32 s18, s20, s42
	v_add_u32_e32 v154, s21, v157
	v_lshl_add_u64 v[174:175], v[174:175], 0, s[6:7]
	s_mov_b32 m0, s18
	ds_read_b128 v[206:209], v154
	ds_read_b128 v[210:213], v154 offset:1024
	ds_read_b128 v[214:217], v154 offset:2048
	ds_read_b128 v[218:221], v154 offset:3072
	global_load_lds_dwordx4 v[174:175], off
	v_lshl_add_u64 v[174:175], v[222:223], 0, s[6:7]
	s_add_i32 m0, s18, 0x2000
	s_nop 0
	global_load_lds_dwordx4 v[174:175], off
	s_barrier
	s_waitcnt lgkmcnt(0)
	s_setprio 1
	s_waitcnt lgkmcnt(0)
	v_mfma_f32_16x16x32_bf16 v[118:121], v[206:209], v[166:169], v[118:121]
	v_mfma_f32_16x16x32_bf16 v[114:117], v[214:217], v[166:169], v[114:117]
	v_mfma_f32_16x16x32_bf16 v[102:105], v[206:209], v[182:185], v[102:105]
	v_mfma_f32_16x16x32_bf16 v[98:101], v[214:217], v[182:185], v[98:101]
	v_mfma_f32_16x16x32_bf16 v[86:89], v[206:209], v[190:193], v[86:89]
	v_mfma_f32_16x16x32_bf16 v[82:85], v[214:217], v[190:193], v[82:85]
	v_mfma_f32_16x16x32_bf16 v[70:73], v[206:209], v[198:201], v[70:73]
	v_mfma_f32_16x16x32_bf16 v[66:69], v[214:217], v[198:201], v[66:69]
	v_mfma_f32_16x16x32_bf16 v[118:121], v[210:213], v[178:181], v[118:121]
	v_mfma_f32_16x16x32_bf16 v[114:117], v[218:221], v[178:181], v[114:117]
	v_mfma_f32_16x16x32_bf16 v[102:105], v[210:213], v[186:189], v[102:105]
	v_mfma_f32_16x16x32_bf16 v[98:101], v[218:221], v[186:189], v[98:101]
	v_mfma_f32_16x16x32_bf16 v[86:89], v[210:213], v[194:197], v[86:89]
	v_mfma_f32_16x16x32_bf16 v[82:85], v[218:221], v[194:197], v[82:85]
	v_mfma_f32_16x16x32_bf16 v[70:73], v[210:213], v[202:205], v[70:73]
	v_mfma_f32_16x16x32_bf16 v[66:69], v[218:221], v[202:205], v[66:69]
	s_setprio 0
	s_mov_b32 m0, s50
	v_lshl_add_u64 v[174:175], v[224:225], 0, s[6:7]
	s_barrier
	ds_read_b128 v[166:169], v173 offset:49152
	ds_read_b128 v[178:181], v173 offset:50176
	ds_read_b128 v[182:185], v173 offset:51200
	ds_read_b128 v[186:189], v173 offset:52224
	ds_read_b128 v[190:193], v173 offset:53248
	ds_read_b128 v[194:197], v173 offset:54272
	ds_read_b128 v[198:201], v173 offset:55296
	ds_read_b128 v[202:205], v173 offset:56320
	global_load_lds_dwordx4 v[174:175], off
	v_lshl_add_u64 v[174:175], v[226:227], 0, s[6:7]
	s_mov_b32 m0, s51
	s_nop 0
	global_load_lds_dwordx4 v[174:175], off
	s_barrier
	s_waitcnt lgkmcnt(0)
	s_setprio 1
	s_waitcnt lgkmcnt(0)
	v_mfma_f32_16x16x32_bf16 v[62:65], v[130:133], v[166:169], v[62:65]
	v_mfma_f32_16x16x32_bf16 v[58:61], v[138:141], v[166:169], v[58:61]
	v_mfma_f32_16x16x32_bf16 v[46:49], v[130:133], v[182:185], v[46:49]
	v_mfma_f32_16x16x32_bf16 v[42:45], v[138:141], v[182:185], v[42:45]
	v_mfma_f32_16x16x32_bf16 v[30:33], v[130:133], v[190:193], v[30:33]
	v_mfma_f32_16x16x32_bf16 v[26:29], v[138:141], v[190:193], v[26:29]
	v_mfma_f32_16x16x32_bf16 v[14:17], v[130:133], v[198:201], v[14:17]
	v_mfma_f32_16x16x32_bf16 v[10:13], v[138:141], v[198:201], v[10:13]
	v_mfma_f32_16x16x32_bf16 v[62:65], v[134:137], v[178:181], v[62:65]
	v_mfma_f32_16x16x32_bf16 v[58:61], v[142:145], v[178:181], v[58:61]
	v_mfma_f32_16x16x32_bf16 v[46:49], v[134:137], v[186:189], v[46:49]
	v_mfma_f32_16x16x32_bf16 v[42:45], v[142:145], v[186:189], v[42:45]
	v_mfma_f32_16x16x32_bf16 v[30:33], v[134:137], v[194:197], v[30:33]
	v_mfma_f32_16x16x32_bf16 v[26:29], v[142:145], v[194:197], v[26:29]
	v_mfma_f32_16x16x32_bf16 v[14:17], v[134:137], v[202:205], v[14:17]
	v_mfma_f32_16x16x32_bf16 v[10:13], v[142:145], v[202:205], v[10:13]
	s_setprio 0
	s_barrier
	s_add_u32 s18, s34, 0x40080
	s_addc_u32 s19, s35, 0
	s_add_i32 s20, s21, s42
	v_lshl_add_u64 v[130:131], s[18:19], 0, v[150:151]
	s_mov_b32 m0, s20
	s_nop 0
	global_load_lds_dwordx4 v[130:131], off
	v_lshl_add_u64 v[130:131], s[18:19], 0, v[146:147]
	s_add_i32 m0, s20, 0x2000
	s_nop 0
	global_load_lds_dwordx4 v[130:131], off
	s_waitcnt vmcnt(6)
	s_barrier
	s_setprio 1
	v_mfma_f32_16x16x32_bf16 v[54:57], v[206:209], v[166:169], v[54:57]
	v_mfma_f32_16x16x32_bf16 v[50:53], v[214:217], v[166:169], v[50:53]
	v_mfma_f32_16x16x32_bf16 v[38:41], v[206:209], v[182:185], v[38:41]
	v_mfma_f32_16x16x32_bf16 v[34:37], v[214:217], v[182:185], v[34:37]
	v_mfma_f32_16x16x32_bf16 v[22:25], v[206:209], v[190:193], v[22:25]
	v_mfma_f32_16x16x32_bf16 v[18:21], v[214:217], v[190:193], v[18:21]
	v_mfma_f32_16x16x32_bf16 v[6:9], v[206:209], v[198:201], v[6:9]
	v_mfma_f32_16x16x32_bf16 v[2:5], v[214:217], v[198:201], v[2:5]
	v_mfma_f32_16x16x32_bf16 v[54:57], v[210:213], v[178:181], v[54:57]
	v_mfma_f32_16x16x32_bf16 v[50:53], v[218:221], v[178:181], v[50:53]
	v_mfma_f32_16x16x32_bf16 v[38:41], v[210:213], v[186:189], v[38:41]
	v_mfma_f32_16x16x32_bf16 v[34:37], v[218:221], v[186:189], v[34:37]
	v_mfma_f32_16x16x32_bf16 v[22:25], v[210:213], v[194:197], v[22:25]
	v_mfma_f32_16x16x32_bf16 v[18:21], v[218:221], v[194:197], v[18:21]
	v_mfma_f32_16x16x32_bf16 v[6:9], v[210:213], v[202:205], v[6:9]
	v_mfma_f32_16x16x32_bf16 v[2:5], v[218:221], v[202:205], v[2:5]
	s_setprio 0
	s_add_i32 s63, s63, 2
	s_add_u32 s24, s24, 0x100
	s_addc_u32 s25, s25, 0
	s_add_u32 s61, s61, 0x100
	s_addc_u32 s62, s62, 0
	s_cmp_gt_u32 s63, 13
	s_barrier
	s_cbranch_scc0 .LBB0_3265
	s_ashr_i32 s9, s16, 3
	s_mul_hi_i32 s11, s9, 0x5800
	s_mulk_i32 s9, 0x5800
	s_add_u32 s9, s48, s9
	s_addc_u32 s11, s49, s11
	s_lshl_b32 s18, s17, 8
	s_ashr_i32 s19, s18, 31
	s_lshl_b64 s[18:19], s[18:19], 2
	v_lshl_add_u32 v180, s16, 8, v1
	s_add_u32 s18, s9, s18
	s_addc_u32 s19, s11, s19
	v_lshlrev_b32_e32 v130, 2, v156
	v_ashrrev_i32_e32 v181, 31, v180
	v_mov_b32_e32 v142, v236
	v_mov_b32_e32 v143, v237
	v_mov_b32_e32 v144, v238
	v_mov_b32_e32 v145, v239
	v_lshl_add_u64 v[182:183], v[180:181], 2, s[4:5]
	v_mov_b32_e32 v190, v228
	v_mov_b32_e32 v138, v240
	v_mov_b32_e32 v139, v241
	v_mov_b32_e32 v140, v242
	v_mov_b32_e32 v141, v243
	v_mov_b32_e32 v134, v244
	v_mov_b32_e32 v135, v245
	v_mov_b32_e32 v136, v246
	v_mov_b32_e32 v137, v247
	s_nop 0
	v_mov_b32_e32 v130, v248
	v_mov_b32_e32 v131, v249
	v_mov_b32_e32 v132, v250
	v_mov_b32_e32 v133, v251
	v_or_b32_e32 v192, 16, v180
	v_ashrrev_i32_e32 v193, 31, v192
	v_lshl_add_u64 v[168:169], v[192:193], 2, s[4:5]
	v_mov_b32_e32 v194, v229
	v_or_b32_e32 v188, 32, v180
	v_or_b32_e32 v184, 48, v180
	v_mov_b64_e32 v[166:167], s[0:1]
	v_add_u32_e32 v178, 0x90, v180
	v_add_u32_e32 v174, 0xa0, v180
	v_add_u32_e32 v168, 0xb0, v180
	v_ashrrev_i32_e32 v189, 31, v188
	v_ashrrev_i32_e32 v185, 31, v184
	v_add_u32_e32 v193, 0x80, v180
	v_mad_i64_i32 v[196:197], s[18:19], v180, s56, v[166:167]
	v_ashrrev_i32_e32 v179, 31, v178
	v_ashrrev_i32_e32 v175, 31, v174
	v_ashrrev_i32_e32 v169, 31, v168
	v_lshl_add_u64 v[180:181], v[188:189], 2, s[4:5]
	v_lshl_add_u64 v[186:187], v[184:185], 2, s[4:5]
	v_lshl_add_u64 v[198:199], v[178:179], 2, s[4:5]
	v_lshl_add_u64 v[200:201], v[174:175], 2, s[4:5]
	v_lshl_add_u64 v[202:203], v[168:169], 2, s[4:5]
	v_mov_b32_e32 v204, v233
	s_nop 0
	v_mov_b32_e32 v186, v234
	s_nop 0
	v_mov_b32_e32 v180, v252
	s_nop 0
	v_mov_b32_e32 v182, v235
	s_lshl_b32 s16, s17, 7
	s_ashr_i32 s17, s16, 31
	s_lshl_b64 s[16:17], s[16:17], 1
	v_lshlrev_b32_e32 v154, 1, v156
	v_lshl_add_u64 v[196:197], v[196:197], 0, s[16:17]
	s_and_b64 vcc, exec, s[2:3]
	s_mov_b64 s[34:35], s[14:15]
	s_mov_b64 s[24:25], s[12:13]
	v_pk_fma_f32 v[118:119], v[118:119], v[190:191], v[138:139] op_sel_hi:[1,0,1]
	v_pk_fma_f32 v[126:127], v[126:127], v[190:191], v[142:143] op_sel_hi:[1,0,1]
	v_pk_fma_f32 v[128:129], v[128:129], v[190:191], v[144:145] op_sel_hi:[1,0,1]
	v_pk_fma_f32 v[122:123], v[122:123], v[190:191], v[134:135] op_sel_hi:[1,0,1]
	v_pk_fma_f32 v[124:125], v[124:125], v[190:191], v[136:137] op_sel_hi:[1,0,1]
	v_mul_f32_e32 v169, 0xbfb8aa3b, v126
	v_mul_f32_e32 v175, 0xbfb8aa3b, v127
	v_mul_f32_e32 v179, 0xbfb8aa3b, v128
	v_mul_f32_e32 v181, 0xbfb8aa3b, v129
	v_mul_f32_e32 v183, 0xbfb8aa3b, v122
	v_mul_f32_e32 v185, 0xbfb8aa3b, v123
	v_mul_f32_e32 v187, 0xbfb8aa3b, v124
	v_mul_f32_e32 v189, 0xbfb8aa3b, v125
	v_exp_f32_e32 v169, v169
	v_exp_f32_e32 v175, v175
	v_exp_f32_e32 v179, v179
	v_exp_f32_e32 v181, v181
	v_exp_f32_e32 v183, v183
	v_exp_f32_e32 v185, v185
	v_exp_f32_e32 v187, v187
	v_exp_f32_e32 v189, v189
	v_add_f32_e32 v169, 1.0, v169
	v_add_f32_e32 v175, 1.0, v175
	v_add_f32_e32 v179, 1.0, v179
	v_add_f32_e32 v181, 1.0, v181
	v_add_f32_e32 v183, 1.0, v183
	v_add_f32_e32 v185, 1.0, v185
	v_add_f32_e32 v187, 1.0, v187
	v_add_f32_e32 v189, 1.0, v189
	v_pk_fma_f32 v[120:121], v[120:121], v[190:191], v[140:141] op_sel_hi:[1,0,1]
	v_pk_fma_f32 v[114:115], v[114:115], v[190:191], v[130:131] op_sel_hi:[1,0,1]
	v_pk_fma_f32 v[116:117], v[116:117], v[190:191], v[132:133] op_sel_hi:[1,0,1]
	v_rcp_f32_e32 v190, v169
	v_rcp_f32_e32 v191, v175
	v_rcp_f32_e32 v198, v179
	v_rcp_f32_e32 v199, v181
	v_rcp_f32_e32 v200, v183
	v_rcp_f32_e32 v201, v185
	v_rcp_f32_e32 v202, v187
	v_rcp_f32_e32 v203, v189
	v_pk_mul_f32 v[126:127], v[126:127], v[190:191]
	v_pk_mul_f32 v[128:129], v[128:129], v[198:199]
	v_pk_mul_f32 v[122:123], v[122:123], v[200:201]
	v_pk_mul_f32 v[124:125], v[124:125], v[202:203]
	v_pk_mul_f32 v[118:119], v[118:119], v[126:127]
	v_pk_mul_f32 v[120:121], v[120:121], v[128:129]
	v_pk_mul_f32 v[122:123], v[114:115], v[122:123]
	v_pk_mul_f32 v[124:125], v[116:117], v[124:125]
	v_pk_fma_f32 v[110:111], v[110:111], v[194:195], v[142:143] op_sel_hi:[1,0,1]
	v_lshl_add_u64 v[126:127], v[196:197], 0, v[154:155]
	v_cvt_pk_bf16_f32 v114, v118, v119
	v_cvt_pk_bf16_f32 v115, v120, v121
	v_cvt_pk_bf16_f32 v116, v122, v123
	v_cvt_pk_bf16_f32 v117, v124, v125
	v_mul_f32_e32 v118, 0xbfb8aa3b, v110
	v_mul_f32_e32 v119, 0xbfb8aa3b, v111
	v_pk_fma_f32 v[112:113], v[112:113], v[194:195], v[144:145] op_sel_hi:[1,0,1]
	v_exp_f32_e32 v118, v118
	v_exp_f32_e32 v119, v119
	global_store_dwordx4 v[126:127], v[114:117], off
	v_pk_fma_f32 v[102:103], v[102:103], v[194:195], v[138:139] op_sel_hi:[1,0,1]
	v_pk_fma_f32 v[106:107], v[106:107], v[194:195], v[134:135] op_sel_hi:[1,0,1]
	v_mul_f32_e32 v116, 0xbfb8aa3b, v112
	v_mul_f32_e32 v117, 0xbfb8aa3b, v113
	v_exp_f32_e32 v116, v116
	v_exp_f32_e32 v117, v117
	v_add_f32_e32 v114, 1.0, v118
	v_add_f32_e32 v115, 1.0, v119
	v_rcp_f32_e32 v114, v114
	v_rcp_f32_e32 v115, v115
	v_add_f32_e32 v116, 1.0, v116
	v_add_f32_e32 v117, 1.0, v117
	v_rcp_f32_e32 v116, v116
	v_rcp_f32_e32 v117, v117
	v_pk_mul_f32 v[110:111], v[110:111], v[114:115]
	v_pk_fma_f32 v[104:105], v[104:105], v[194:195], v[140:141] op_sel_hi:[1,0,1]
	v_pk_mul_f32 v[102:103], v[102:103], v[110:111]
	v_pk_mul_f32 v[110:111], v[112:113], v[116:117]
	v_mul_f32_e32 v112, 0xbfb8aa3b, v106
	v_mul_f32_e32 v113, 0xbfb8aa3b, v107
	v_exp_f32_e32 v112, v112
	v_exp_f32_e32 v113, v113
	v_pk_fma_f32 v[108:109], v[108:109], v[194:195], v[136:137] op_sel_hi:[1,0,1]
	v_pk_mul_f32 v[104:105], v[104:105], v[110:111]
	v_add_f32_e32 v110, 1.0, v112
	v_add_f32_e32 v111, 1.0, v113
	v_mul_f32_e32 v112, 0xbfb8aa3b, v108
	v_mul_f32_e32 v113, 0xbfb8aa3b, v109
	v_exp_f32_e32 v112, v112
	v_exp_f32_e32 v113, v113
	v_rcp_f32_e32 v110, v110
	v_rcp_f32_e32 v111, v111
	v_add_f32_e32 v112, 1.0, v112
	v_add_f32_e32 v113, 1.0, v113
	v_rcp_f32_e32 v112, v112
	v_rcp_f32_e32 v113, v113
	v_pk_mul_f32 v[106:107], v[106:107], v[110:111]
	v_pk_fma_f32 v[98:99], v[98:99], v[194:195], v[130:131] op_sel_hi:[1,0,1]
	v_pk_fma_f32 v[100:101], v[100:101], v[194:195], v[132:133] op_sel_hi:[1,0,1]
	v_pk_mul_f32 v[106:107], v[98:99], v[106:107]
	v_pk_mul_f32 v[98:99], v[108:109], v[112:113]
	v_pk_fma_f32 v[94:95], v[94:95], v[204:205], v[142:143] op_sel_hi:[1,0,1]
	v_pk_mul_f32 v[108:109], v[100:101], v[98:99]
	v_mad_i64_i32 v[98:99], s[18:19], v192, s56, v[166:167]
	v_lshl_add_u64 v[98:99], v[98:99], 0, s[16:17]
	v_lshl_add_u64 v[110:111], v[98:99], 0, v[154:155]
	v_cvt_pk_bf16_f32 v98, v102, v103
	v_cvt_pk_bf16_f32 v99, v104, v105
	v_cvt_pk_bf16_f32 v100, v106, v107
	v_cvt_pk_bf16_f32 v101, v108, v109
	v_mul_f32_e32 v102, 0xbfb8aa3b, v94
	v_mul_f32_e32 v103, 0xbfb8aa3b, v95
	v_pk_fma_f32 v[96:97], v[96:97], v[204:205], v[144:145] op_sel_hi:[1,0,1]
	v_exp_f32_e32 v102, v102
	v_exp_f32_e32 v103, v103
	global_store_dwordx4 v[110:111], v[98:101], off
	v_pk_fma_f32 v[86:87], v[86:87], v[204:205], v[138:139] op_sel_hi:[1,0,1]
	v_pk_fma_f32 v[90:91], v[90:91], v[204:205], v[134:135] op_sel_hi:[1,0,1]
	v_mul_f32_e32 v100, 0xbfb8aa3b, v96
	v_mul_f32_e32 v101, 0xbfb8aa3b, v97
	v_exp_f32_e32 v100, v100
	v_exp_f32_e32 v101, v101
	v_add_f32_e32 v98, 1.0, v102
	v_add_f32_e32 v99, 1.0, v103
	v_rcp_f32_e32 v98, v98
	v_rcp_f32_e32 v99, v99
	v_add_f32_e32 v100, 1.0, v100
	v_add_f32_e32 v101, 1.0, v101
	v_rcp_f32_e32 v100, v100
	v_rcp_f32_e32 v101, v101
	v_pk_mul_f32 v[94:95], v[94:95], v[98:99]
	v_pk_fma_f32 v[88:89], v[88:89], v[204:205], v[140:141] op_sel_hi:[1,0,1]
	v_pk_mul_f32 v[86:87], v[86:87], v[94:95]
	v_pk_mul_f32 v[94:95], v[96:97], v[100:101]
	v_mul_f32_e32 v96, 0xbfb8aa3b, v90
	v_mul_f32_e32 v97, 0xbfb8aa3b, v91
	v_exp_f32_e32 v96, v96
	v_exp_f32_e32 v97, v97
	v_pk_fma_f32 v[92:93], v[92:93], v[204:205], v[136:137] op_sel_hi:[1,0,1]
	v_pk_mul_f32 v[88:89], v[88:89], v[94:95]
	v_add_f32_e32 v94, 1.0, v96
	v_add_f32_e32 v95, 1.0, v97
	v_mul_f32_e32 v96, 0xbfb8aa3b, v92
	v_mul_f32_e32 v97, 0xbfb8aa3b, v93
	v_exp_f32_e32 v96, v96
	v_exp_f32_e32 v97, v97
	v_rcp_f32_e32 v94, v94
	v_rcp_f32_e32 v95, v95
	v_add_f32_e32 v96, 1.0, v96
	v_add_f32_e32 v97, 1.0, v97
	v_rcp_f32_e32 v96, v96
	v_rcp_f32_e32 v97, v97
	v_pk_mul_f32 v[90:91], v[90:91], v[94:95]
	v_pk_fma_f32 v[82:83], v[82:83], v[204:205], v[130:131] op_sel_hi:[1,0,1]
	v_pk_fma_f32 v[84:85], v[84:85], v[204:205], v[132:133] op_sel_hi:[1,0,1]
	v_pk_mul_f32 v[90:91], v[82:83], v[90:91]
	v_pk_mul_f32 v[82:83], v[92:93], v[96:97]
	v_pk_fma_f32 v[78:79], v[78:79], v[186:187], v[142:143] op_sel_hi:[1,0,1]
	v_pk_mul_f32 v[92:93], v[84:85], v[82:83]
	v_mad_i64_i32 v[82:83], s[18:19], v188, s56, v[166:167]
	v_lshl_add_u64 v[82:83], v[82:83], 0, s[16:17]
	v_lshl_add_u64 v[94:95], v[82:83], 0, v[154:155]
	v_cvt_pk_bf16_f32 v82, v86, v87
	v_cvt_pk_bf16_f32 v83, v88, v89
	v_cvt_pk_bf16_f32 v84, v90, v91
	v_cvt_pk_bf16_f32 v85, v92, v93
	v_mul_f32_e32 v86, 0xbfb8aa3b, v78
	v_mul_f32_e32 v87, 0xbfb8aa3b, v79
	v_pk_fma_f32 v[80:81], v[80:81], v[186:187], v[144:145] op_sel_hi:[1,0,1]
	v_exp_f32_e32 v86, v86
	v_exp_f32_e32 v87, v87
	global_store_dwordx4 v[94:95], v[82:85], off
	v_pk_fma_f32 v[70:71], v[70:71], v[186:187], v[138:139] op_sel_hi:[1,0,1]
	v_pk_fma_f32 v[74:75], v[74:75], v[186:187], v[134:135] op_sel_hi:[1,0,1]
	v_mul_f32_e32 v84, 0xbfb8aa3b, v80
	v_mul_f32_e32 v85, 0xbfb8aa3b, v81
	v_exp_f32_e32 v84, v84
	v_exp_f32_e32 v85, v85
	v_add_f32_e32 v82, 1.0, v86
	v_add_f32_e32 v83, 1.0, v87
	v_rcp_f32_e32 v82, v82
	v_rcp_f32_e32 v83, v83
	v_add_f32_e32 v84, 1.0, v84
	v_add_f32_e32 v85, 1.0, v85
	v_rcp_f32_e32 v84, v84
	v_rcp_f32_e32 v85, v85
	v_pk_mul_f32 v[78:79], v[78:79], v[82:83]
	v_pk_fma_f32 v[72:73], v[72:73], v[186:187], v[140:141] op_sel_hi:[1,0,1]
	v_pk_mul_f32 v[70:71], v[70:71], v[78:79]
	v_pk_mul_f32 v[78:79], v[80:81], v[84:85]
	v_mul_f32_e32 v80, 0xbfb8aa3b, v74
	v_mul_f32_e32 v81, 0xbfb8aa3b, v75
	v_exp_f32_e32 v80, v80
	v_exp_f32_e32 v81, v81
	v_pk_fma_f32 v[76:77], v[76:77], v[186:187], v[136:137] op_sel_hi:[1,0,1]
	v_pk_mul_f32 v[72:73], v[72:73], v[78:79]
	v_add_f32_e32 v78, 1.0, v80
	v_add_f32_e32 v79, 1.0, v81
	v_mul_f32_e32 v80, 0xbfb8aa3b, v76
	v_mul_f32_e32 v81, 0xbfb8aa3b, v77
	v_exp_f32_e32 v80, v80
	v_exp_f32_e32 v81, v81
	v_rcp_f32_e32 v78, v78
	v_rcp_f32_e32 v79, v79
	v_add_f32_e32 v80, 1.0, v80
	v_add_f32_e32 v81, 1.0, v81
	v_rcp_f32_e32 v80, v80
	v_rcp_f32_e32 v81, v81
	v_pk_mul_f32 v[74:75], v[74:75], v[78:79]
	v_pk_fma_f32 v[66:67], v[66:67], v[186:187], v[130:131] op_sel_hi:[1,0,1]
	v_pk_fma_f32 v[68:69], v[68:69], v[186:187], v[132:133] op_sel_hi:[1,0,1]
	v_pk_mul_f32 v[74:75], v[66:67], v[74:75]
	v_pk_mul_f32 v[66:67], v[76:77], v[80:81]
	v_pk_fma_f32 v[62:63], v[62:63], v[182:183], v[142:143] op_sel_hi:[1,0,1]
	v_pk_mul_f32 v[76:77], v[68:69], v[66:67]
	v_mad_i64_i32 v[66:67], s[18:19], v184, s56, v[166:167]
	v_lshl_add_u64 v[66:67], v[66:67], 0, s[16:17]
	v_lshl_add_u64 v[78:79], v[66:67], 0, v[154:155]
	v_cvt_pk_bf16_f32 v66, v70, v71
	v_cvt_pk_bf16_f32 v67, v72, v73
	v_cvt_pk_bf16_f32 v68, v74, v75
	v_cvt_pk_bf16_f32 v69, v76, v77
	v_mul_f32_e32 v70, 0xbfb8aa3b, v62
	v_mul_f32_e32 v71, 0xbfb8aa3b, v63
	v_pk_fma_f32 v[64:65], v[64:65], v[182:183], v[144:145] op_sel_hi:[1,0,1]
	v_exp_f32_e32 v70, v70
	v_exp_f32_e32 v71, v71
	global_store_dwordx4 v[78:79], v[66:69], off
	v_pk_fma_f32 v[54:55], v[54:55], v[182:183], v[138:139] op_sel_hi:[1,0,1]
	v_pk_fma_f32 v[58:59], v[58:59], v[182:183], v[134:135] op_sel_hi:[1,0,1]
	v_mul_f32_e32 v68, 0xbfb8aa3b, v64
	v_mul_f32_e32 v69, 0xbfb8aa3b, v65
	v_exp_f32_e32 v68, v68
	v_exp_f32_e32 v69, v69
	v_add_f32_e32 v66, 1.0, v70
	v_add_f32_e32 v67, 1.0, v71
	v_rcp_f32_e32 v66, v66
	v_rcp_f32_e32 v67, v67
	v_add_f32_e32 v68, 1.0, v68
	v_add_f32_e32 v69, 1.0, v69
	v_rcp_f32_e32 v68, v68
	v_rcp_f32_e32 v69, v69
	v_pk_mul_f32 v[62:63], v[62:63], v[66:67]
	v_pk_fma_f32 v[56:57], v[56:57], v[182:183], v[140:141] op_sel_hi:[1,0,1]
	v_pk_mul_f32 v[54:55], v[54:55], v[62:63]
	v_pk_mul_f32 v[62:63], v[64:65], v[68:69]
	v_mul_f32_e32 v64, 0xbfb8aa3b, v58
	v_mul_f32_e32 v65, 0xbfb8aa3b, v59
	v_exp_f32_e32 v64, v64
	v_exp_f32_e32 v65, v65
	v_pk_fma_f32 v[60:61], v[60:61], v[182:183], v[136:137] op_sel_hi:[1,0,1]
	v_pk_mul_f32 v[56:57], v[56:57], v[62:63]
	v_add_f32_e32 v62, 1.0, v64
	v_add_f32_e32 v63, 1.0, v65
	v_mul_f32_e32 v64, 0xbfb8aa3b, v60
	v_mul_f32_e32 v65, 0xbfb8aa3b, v61
	v_exp_f32_e32 v64, v64
	v_exp_f32_e32 v65, v65
	v_rcp_f32_e32 v62, v62
	v_rcp_f32_e32 v63, v63
	v_add_f32_e32 v64, 1.0, v64
	v_add_f32_e32 v65, 1.0, v65
	v_rcp_f32_e32 v64, v64
	v_rcp_f32_e32 v65, v65
	v_pk_mul_f32 v[58:59], v[58:59], v[62:63]
	v_pk_fma_f32 v[50:51], v[50:51], v[182:183], v[130:131] op_sel_hi:[1,0,1]
	v_pk_fma_f32 v[52:53], v[52:53], v[182:183], v[132:133] op_sel_hi:[1,0,1]
	v_pk_mul_f32 v[58:59], v[50:51], v[58:59]
	v_pk_mul_f32 v[50:51], v[60:61], v[64:65]
	v_pk_fma_f32 v[46:47], v[46:47], v[180:181], v[142:143] op_sel_hi:[1,0,1]
	v_pk_mul_f32 v[60:61], v[52:53], v[50:51]
	v_mad_i64_i32 v[50:51], s[18:19], v193, s56, v[166:167]
	v_lshl_add_u64 v[50:51], v[50:51], 0, s[16:17]
	v_lshl_add_u64 v[62:63], v[50:51], 0, v[154:155]
	v_cvt_pk_bf16_f32 v50, v54, v55
	v_cvt_pk_bf16_f32 v51, v56, v57
	v_cvt_pk_bf16_f32 v52, v58, v59
	v_cvt_pk_bf16_f32 v53, v60, v61
	v_mul_f32_e32 v54, 0xbfb8aa3b, v46
	v_mul_f32_e32 v55, 0xbfb8aa3b, v47
	v_pk_fma_f32 v[48:49], v[48:49], v[180:181], v[144:145] op_sel_hi:[1,0,1]
	v_exp_f32_e32 v54, v54
	v_exp_f32_e32 v55, v55
	global_store_dwordx4 v[62:63], v[50:53], off
	v_pk_fma_f32 v[38:39], v[38:39], v[180:181], v[138:139] op_sel_hi:[1,0,1]
	v_pk_fma_f32 v[42:43], v[42:43], v[180:181], v[134:135] op_sel_hi:[1,0,1]
	v_mul_f32_e32 v52, 0xbfb8aa3b, v48
	v_mul_f32_e32 v53, 0xbfb8aa3b, v49
	v_exp_f32_e32 v52, v52
	v_exp_f32_e32 v53, v53
	v_add_f32_e32 v50, 1.0, v54
	v_add_f32_e32 v51, 1.0, v55
	v_rcp_f32_e32 v50, v50
	v_rcp_f32_e32 v51, v51
	v_add_f32_e32 v52, 1.0, v52
	v_add_f32_e32 v53, 1.0, v53
	v_rcp_f32_e32 v52, v52
	v_rcp_f32_e32 v53, v53
	v_pk_mul_f32 v[46:47], v[46:47], v[50:51]
	v_pk_fma_f32 v[40:41], v[40:41], v[180:181], v[140:141] op_sel_hi:[1,0,1]
	v_pk_mul_f32 v[38:39], v[38:39], v[46:47]
	v_pk_mul_f32 v[46:47], v[48:49], v[52:53]
	v_mul_f32_e32 v48, 0xbfb8aa3b, v42
	v_mul_f32_e32 v49, 0xbfb8aa3b, v43
	v_exp_f32_e32 v48, v48
	v_exp_f32_e32 v49, v49
	v_pk_fma_f32 v[44:45], v[44:45], v[180:181], v[136:137] op_sel_hi:[1,0,1]
	v_pk_mul_f32 v[40:41], v[40:41], v[46:47]
	v_add_f32_e32 v46, 1.0, v48
	v_add_f32_e32 v47, 1.0, v49
	v_mul_f32_e32 v48, 0xbfb8aa3b, v44
	v_mul_f32_e32 v49, 0xbfb8aa3b, v45
	v_exp_f32_e32 v48, v48
	v_exp_f32_e32 v49, v49
	v_rcp_f32_e32 v46, v46
	v_rcp_f32_e32 v47, v47
	v_add_f32_e32 v48, 1.0, v48
	v_add_f32_e32 v49, 1.0, v49
	v_rcp_f32_e32 v48, v48
	v_rcp_f32_e32 v49, v49
	v_pk_mul_f32 v[42:43], v[42:43], v[46:47]
	v_pk_fma_f32 v[34:35], v[34:35], v[180:181], v[130:131] op_sel_hi:[1,0,1]
	v_pk_fma_f32 v[36:37], v[36:37], v[180:181], v[132:133] op_sel_hi:[1,0,1]
	v_pk_mul_f32 v[42:43], v[34:35], v[42:43]
	v_pk_mul_f32 v[34:35], v[44:45], v[48:49]
	v_pk_fma_f32 v[30:31], v[30:31], v[176:177], v[142:143] op_sel_hi:[1,0,1]
	v_pk_mul_f32 v[44:45], v[36:37], v[34:35]
	v_mad_i64_i32 v[34:35], s[18:19], v178, s56, v[166:167]
	v_lshl_add_u64 v[34:35], v[34:35], 0, s[16:17]
	v_lshl_add_u64 v[46:47], v[34:35], 0, v[154:155]
	v_cvt_pk_bf16_f32 v34, v38, v39
	v_cvt_pk_bf16_f32 v35, v40, v41
	v_cvt_pk_bf16_f32 v36, v42, v43
	v_cvt_pk_bf16_f32 v37, v44, v45
	v_mul_f32_e32 v38, 0xbfb8aa3b, v30
	v_mul_f32_e32 v39, 0xbfb8aa3b, v31
	v_pk_fma_f32 v[32:33], v[32:33], v[176:177], v[144:145] op_sel_hi:[1,0,1]
	v_exp_f32_e32 v38, v38
	v_exp_f32_e32 v39, v39
	global_store_dwordx4 v[46:47], v[34:37], off
	v_pk_fma_f32 v[22:23], v[22:23], v[176:177], v[138:139] op_sel_hi:[1,0,1]
	v_pk_fma_f32 v[26:27], v[26:27], v[176:177], v[134:135] op_sel_hi:[1,0,1]
	v_mul_f32_e32 v36, 0xbfb8aa3b, v32
	v_mul_f32_e32 v37, 0xbfb8aa3b, v33
	v_exp_f32_e32 v36, v36
	v_exp_f32_e32 v37, v37
	v_add_f32_e32 v34, 1.0, v38
	v_add_f32_e32 v35, 1.0, v39
	v_rcp_f32_e32 v34, v34
	v_rcp_f32_e32 v35, v35
	v_add_f32_e32 v36, 1.0, v36
	v_add_f32_e32 v37, 1.0, v37
	v_rcp_f32_e32 v36, v36
	v_rcp_f32_e32 v37, v37
	v_pk_mul_f32 v[30:31], v[30:31], v[34:35]
	v_pk_fma_f32 v[24:25], v[24:25], v[176:177], v[140:141] op_sel_hi:[1,0,1]
	v_pk_mul_f32 v[22:23], v[22:23], v[30:31]
	v_pk_mul_f32 v[30:31], v[32:33], v[36:37]
	v_mul_f32_e32 v32, 0xbfb8aa3b, v26
	v_mul_f32_e32 v33, 0xbfb8aa3b, v27
	v_exp_f32_e32 v32, v32
	v_exp_f32_e32 v33, v33
	v_pk_fma_f32 v[28:29], v[28:29], v[176:177], v[136:137] op_sel_hi:[1,0,1]
	v_pk_mul_f32 v[24:25], v[24:25], v[30:31]
	v_add_f32_e32 v30, 1.0, v32
	v_add_f32_e32 v31, 1.0, v33
	v_mul_f32_e32 v32, 0xbfb8aa3b, v28
	v_mul_f32_e32 v33, 0xbfb8aa3b, v29
	v_exp_f32_e32 v32, v32
	v_exp_f32_e32 v33, v33
	v_rcp_f32_e32 v30, v30
	v_rcp_f32_e32 v31, v31
	v_add_f32_e32 v32, 1.0, v32
	v_add_f32_e32 v33, 1.0, v33
	v_rcp_f32_e32 v32, v32
	v_rcp_f32_e32 v33, v33
	v_pk_mul_f32 v[26:27], v[26:27], v[30:31]
	v_pk_fma_f32 v[18:19], v[18:19], v[176:177], v[130:131] op_sel_hi:[1,0,1]
	v_pk_fma_f32 v[20:21], v[20:21], v[176:177], v[132:133] op_sel_hi:[1,0,1]
	v_pk_mul_f32 v[26:27], v[18:19], v[26:27]
	v_pk_mul_f32 v[18:19], v[28:29], v[32:33]
	v_pk_fma_f32 v[14:15], v[14:15], v[172:173], v[142:143] op_sel_hi:[1,0,1]
	v_pk_mul_f32 v[28:29], v[20:21], v[18:19]
	v_mad_i64_i32 v[18:19], s[18:19], v174, s56, v[166:167]
	v_lshl_add_u64 v[18:19], v[18:19], 0, s[16:17]
	v_lshl_add_u64 v[30:31], v[18:19], 0, v[154:155]
	v_cvt_pk_bf16_f32 v18, v22, v23
	v_cvt_pk_bf16_f32 v19, v24, v25
	v_cvt_pk_bf16_f32 v20, v26, v27
	v_cvt_pk_bf16_f32 v21, v28, v29
	v_mul_f32_e32 v22, 0xbfb8aa3b, v14
	v_mul_f32_e32 v23, 0xbfb8aa3b, v15
	v_pk_fma_f32 v[16:17], v[16:17], v[172:173], v[144:145] op_sel_hi:[1,0,1]
	v_exp_f32_e32 v22, v22
	v_exp_f32_e32 v23, v23
	global_store_dwordx4 v[30:31], v[18:21], off
	v_pk_fma_f32 v[6:7], v[6:7], v[172:173], v[138:139] op_sel_hi:[1,0,1]
	v_pk_fma_f32 v[10:11], v[10:11], v[172:173], v[134:135] op_sel_hi:[1,0,1]
	v_mul_f32_e32 v20, 0xbfb8aa3b, v16
	v_mul_f32_e32 v21, 0xbfb8aa3b, v17
	v_exp_f32_e32 v20, v20
	v_exp_f32_e32 v21, v21
	v_add_f32_e32 v18, 1.0, v22
	v_add_f32_e32 v19, 1.0, v23
	v_rcp_f32_e32 v18, v18
	v_rcp_f32_e32 v19, v19
	v_add_f32_e32 v20, 1.0, v20
	v_add_f32_e32 v21, 1.0, v21
	v_rcp_f32_e32 v20, v20
	v_rcp_f32_e32 v21, v21
	v_pk_mul_f32 v[14:15], v[14:15], v[18:19]
	v_pk_fma_f32 v[8:9], v[8:9], v[172:173], v[140:141] op_sel_hi:[1,0,1]
	v_pk_mul_f32 v[6:7], v[6:7], v[14:15]
	v_pk_mul_f32 v[14:15], v[16:17], v[20:21]
	v_mul_f32_e32 v16, 0xbfb8aa3b, v10
	v_mul_f32_e32 v17, 0xbfb8aa3b, v11
	v_exp_f32_e32 v16, v16
	v_exp_f32_e32 v17, v17
	v_pk_fma_f32 v[12:13], v[12:13], v[172:173], v[136:137] op_sel_hi:[1,0,1]
	v_pk_mul_f32 v[8:9], v[8:9], v[14:15]
	v_add_f32_e32 v14, 1.0, v16
	v_add_f32_e32 v15, 1.0, v17
	v_mul_f32_e32 v16, 0xbfb8aa3b, v12
	v_mul_f32_e32 v17, 0xbfb8aa3b, v13
	v_exp_f32_e32 v16, v16
	v_exp_f32_e32 v17, v17
	v_rcp_f32_e32 v14, v14
	v_rcp_f32_e32 v15, v15
	v_add_f32_e32 v16, 1.0, v16
	v_add_f32_e32 v17, 1.0, v17
	v_rcp_f32_e32 v16, v16
	v_rcp_f32_e32 v17, v17
	v_pk_mul_f32 v[10:11], v[10:11], v[14:15]
	v_pk_fma_f32 v[2:3], v[2:3], v[172:173], v[130:131] op_sel_hi:[1,0,1]
	v_pk_fma_f32 v[4:5], v[4:5], v[172:173], v[132:133] op_sel_hi:[1,0,1]
	v_pk_mul_f32 v[10:11], v[2:3], v[10:11]
	v_pk_mul_f32 v[2:3], v[12:13], v[16:17]
	s_nop 0
	v_pk_mul_f32 v[12:13], v[4:5], v[2:3]
	v_mad_i64_i32 v[2:3], s[18:19], v168, s56, v[166:167]
	v_lshl_add_u64 v[2:3], v[2:3], 0, s[16:17]
	v_lshl_add_u64 v[14:15], v[2:3], 0, v[154:155]
	v_cvt_pk_bf16_f32 v2, v6, v7
	v_cvt_pk_bf16_f32 v3, v8, v9
	v_cvt_pk_bf16_f32 v4, v10, v11
	v_cvt_pk_bf16_f32 v5, v12, v13
	s_mov_b32 s17, s8
	s_mov_b32 s16, s10
	global_store_dwordx4 v[14:15], v[2:5], off
	s_cbranch_vccz .LBB0_3262
	s_waitcnt vmcnt(0)
	s_cmpk_gt_u32 s33, 0xff
	s_cbranch_scc1 .LBB0_3269
	s_barrier
